# v38 + phase-0 trailing cooperative-groups grid sync replaced by the XCD barrier used by all other phases
# speedup vs baseline: 1.0016x; 1.0016x over previous
; #define LAS __attribute__((address_space(3)))
; __device__ __forceinline__ unsigned xb_ld(unsigned* p)              { return __hip_atomic_load(p, __ATOMIC_RELAXED, __HIP_MEMORY_SCOPE_AGENT); }
; __device__ __forceinline__ unsigned xb_xcc_id() { return (unsigned)__builtin_amdgcn_s_getreg((3 << 11) | 20) & 0xFu; }
; __device__ __forceinline__ void xcd_barrier_complete(unsigned* bar, unsigned x, unsigned& nloc, unsigned& nx) {
;     const unsigned G = gridDim.x * gridDim.y * gridDim.z;
;     unsigned sum, cnt, mine, sp = 0u;
;     for (;;) {
;         sum = 0u; cnt = 0u; mine = 0u;
; #pragma unroll
;         for (unsigned j = 0; j < 16; ++j) { const unsigned c = xb_ld(&bar[XB_XCNT(j)]); sum += c; cnt += (c > 0u) ? 1u : 0u; mine = (j == x) ? c : mine; }
; __device__ __forceinline__ void xcd_barrier(unsigned* bar, volatile LAS unsigned* st) {
;     asm volatile("s_waitcnt vmcnt(0)" ::: "memory");
;     __syncthreads();
;     if (threadIdx.x == 0) {
;         const unsigned x = xb_xcc_id();
;         __builtin_amdgcn_s_waitcnt(0);
;         unsigned nloc = st[0], nx = st[1];
;         if (nloc == 0u) { xcd_barrier_complete(bar, x, nloc, nx); st[0] = nloc; st[1] = nx; }
.LBB0_477:
	v_readlane_b32 s0, v254, 28
	v_readlane_b32 s1, v254, 29
	s_and_b64 vcc, exec, s[0:1]
	s_waitcnt vmcnt(0)
	s_waitcnt vmcnt(0) lgkmcnt(0)
	s_barrier
	s_mov_b64 s[0:1], exec
	v_readlane_b32 s4, v254, 0
	v_readlane_b32 s5, v254, 1
	s_and_b64 s[4:5], s[0:1], s[4:5]
	s_mov_b64 exec, s[4:5]
	s_cbranch_execz .LBB0_532
	v_readlane_b32 s5, v254, 3
	s_getreg_b32 s4, hwreg(HW_REG_XCC_ID, 0, 4)
	s_waitcnt vmcnt(0) expcnt(0) lgkmcnt(0)
	v_mov_b32_e32 v0, s5
	ds_read_b32 v3, v0
	v_readlane_b32 s5, v254, 4
	s_and_b32 s14, s4, 15
	s_waitcnt lgkmcnt(0)
	v_cmp_ne_u32_e32 vcc, 0, v3
	v_mov_b32_e32 v0, s5
	ds_read_b32 v2, v0
	s_cbranch_vccnz .LBB0_496
	s_load_dwordx2 s[8:9], s[94:95], 0x0
	s_load_dword s7, s[94:95], 0x8
	s_add_u32 s4, s42, 0x31046200
	s_addc_u32 s5, s43, 0
	s_add_u32 s6, s42, 0x31046400
	s_waitcnt lgkmcnt(0)
	s_mul_i32 s15, s9, s8
	s_mul_i32 s15, s15, s7
	s_addc_u32 s7, s43, 0
	s_add_u32 s8, s42, 0x31046500
	s_addc_u32 s9, s43, 0
	s_add_u32 s10, s42, 0x31046600
	s_addc_u32 s11, s43, 0
	s_add_u32 s12, s42, 0x31046700
	s_addc_u32 s13, s43, 0
	s_add_u32 s16, s42, 0x31046800
	s_addc_u32 s17, s43, 0
	s_add_u32 s18, s42, 0x31046900
	s_addc_u32 s19, s43, 0
	s_add_u32 s20, s42, 0x31046a00
	s_addc_u32 s21, s43, 0
	s_add_u32 s22, s42, 0x31046b00
	s_addc_u32 s23, s43, 0
	s_add_u32 s24, s42, 0x31046c00
	s_addc_u32 s25, s43, 0
	s_add_u32 s26, s42, 0x31046d00
	s_addc_u32 s27, s43, 0
	s_add_u32 s28, s42, 0x31046e00
	s_addc_u32 s29, s43, 0
	s_add_u32 s30, s42, 0x31046f00
	s_addc_u32 s31, s43, 0
	s_add_u32 s34, s42, 0x31047000
	s_addc_u32 s35, s43, 0
	s_add_u32 s36, s42, 0x31047100
	s_addc_u32 s37, s43, 0
	s_add_u32 s38, s42, 0x31047200
	s_addc_u32 s39, s43, 0
	s_add_u32 s40, s42, 0x31047300
	s_mov_b64 s[54:55], s[42:43]
	s_addc_u32 s41, s43, 0
	s_mov_b32 s52, 1
	s_branch .LBB0_483
